# carry phase hand-written: aggregate loads issued up front (62 + 24) with counted waits instead of ~4 in flight; stores after the fma chain
# baseline (speedup 1.0000x reference)
.LBB0_394:
	s_andn2_b64 vcc, exec, s[6:7]
	s_cbranch_vccnz .LBB0_422
	v_readlane_b32 s6, v254, 0
	v_readlane_b32 s7, v254, 1
	v_mov_b32_e32 v0, v192
	s_load_dwordx4 s[8:11], s[6:7], 0xb8
	s_movk_i32 s6, 0x3000
	v_lshrrev_b32_e32 v1, 6, v0
	v_mul_lo_u32 v1, v1, s42
	v_add_u32_e32 v1, s2, v1
	v_and_b32_e32 v0, 63, v0
	v_lshl_or_b32 v0, v1, 6, v0
	v_cmp_gt_i32_e32 vcc, s6, v0
	s_and_saveexec_b64 s[6:7], vcc
	s_cbranch_execz .LBB0_397
	s_waitcnt lgkmcnt(0)
	s_mov_b32 s100, 0x2aaaaaab
	v_mul_hi_i32 v1, v0, s100
	v_lshrrev_b32_e32 v2, 31, v1
	v_ashrrev_i32_e32 v1, 8, v1
	v_add_u32_e32 v1, v1, v2
	v_mul_i32_i24_e32 v2, 0x600, v1
	v_sub_u32_e32 v0, v0, v2
	v_lshlrev_b32_e32 v0, 2, v0
	s_mov_b32 s100, 0x40800
	v_mul_lo_u32 v1, v1, s100
	v_add_u32_e32 v0, v0, v1
	v_add_u32_e32 v1, 0x39ac000, v0
	v_add_u32_e32 v0, 0x37a8000, v0
	global_load_dword v2, v0, s[8:9]
	global_load_dword v45, v1, s[8:9]
	v_add_u32_e32 v0, 0x1800, v0
	v_add_u32_e32 v1, 0x1800, v1
	global_load_dword v3, v0, s[8:9]
	global_load_dword v46, v1, s[8:9]
	v_add_u32_e32 v0, 0x1800, v0
	v_add_u32_e32 v1, 0x1800, v1
	global_load_dword v4, v0, s[8:9]
	global_load_dword v47, v1, s[8:9]
	v_add_u32_e32 v0, 0x1800, v0
	v_add_u32_e32 v1, 0x1800, v1
	global_load_dword v5, v0, s[8:9]
	global_load_dword v48, v1, s[8:9]
	v_add_u32_e32 v0, 0x1800, v0
	v_add_u32_e32 v1, 0x1800, v1
	global_load_dword v6, v0, s[8:9]
	global_load_dword v49, v1, s[8:9]
	v_add_u32_e32 v0, 0x1800, v0
	v_add_u32_e32 v1, 0x1800, v1
	global_load_dword v7, v0, s[8:9]
	global_load_dword v50, v1, s[8:9]
	v_add_u32_e32 v0, 0x1800, v0
	v_add_u32_e32 v1, 0x1800, v1
	global_load_dword v8, v0, s[8:9]
	global_load_dword v51, v1, s[8:9]
	v_add_u32_e32 v0, 0x1800, v0
	v_add_u32_e32 v1, 0x1800, v1
	global_load_dword v9, v0, s[8:9]
	global_load_dword v52, v1, s[8:9]
	v_add_u32_e32 v0, 0x1800, v0
	v_add_u32_e32 v1, 0x1800, v1
	global_load_dword v10, v0, s[8:9]
	global_load_dword v53, v1, s[8:9]
	v_add_u32_e32 v0, 0x1800, v0
	v_add_u32_e32 v1, 0x1800, v1
	global_load_dword v11, v0, s[8:9]
	global_load_dword v54, v1, s[8:9]
	v_add_u32_e32 v0, 0x1800, v0
	v_add_u32_e32 v1, 0x1800, v1
	global_load_dword v12, v0, s[8:9]
	global_load_dword v55, v1, s[8:9]
	v_add_u32_e32 v0, 0x1800, v0
	v_add_u32_e32 v1, 0x1800, v1
	global_load_dword v13, v0, s[8:9]
	global_load_dword v56, v1, s[8:9]
	v_add_u32_e32 v0, 0x1800, v0
	v_add_u32_e32 v1, 0x1800, v1
	global_load_dword v14, v0, s[8:9]
	global_load_dword v57, v1, s[8:9]
	v_add_u32_e32 v0, 0x1800, v0
	v_add_u32_e32 v1, 0x1800, v1
	global_load_dword v15, v0, s[8:9]
	global_load_dword v58, v1, s[8:9]
	v_add_u32_e32 v0, 0x1800, v0
	v_add_u32_e32 v1, 0x1800, v1
	global_load_dword v16, v0, s[8:9]
	global_load_dword v59, v1, s[8:9]
	v_add_u32_e32 v0, 0x1800, v0
	v_add_u32_e32 v1, 0x1800, v1
	global_load_dword v17, v0, s[8:9]
	global_load_dword v60, v1, s[8:9]
	v_add_u32_e32 v0, 0x1800, v0
	v_add_u32_e32 v1, 0x1800, v1
	global_load_dword v18, v0, s[8:9]
	global_load_dword v61, v1, s[8:9]
	v_add_u32_e32 v0, 0x1800, v0
	v_add_u32_e32 v1, 0x1800, v1
	global_load_dword v19, v0, s[8:9]
	global_load_dword v62, v1, s[8:9]
	v_add_u32_e32 v0, 0x1800, v0
	v_add_u32_e32 v1, 0x1800, v1
	global_load_dword v20, v0, s[8:9]
	global_load_dword v63, v1, s[8:9]
	v_add_u32_e32 v0, 0x1800, v0
	v_add_u32_e32 v1, 0x1800, v1
	global_load_dword v21, v0, s[8:9]
	global_load_dword v64, v1, s[8:9]
	v_add_u32_e32 v0, 0x1800, v0
	v_add_u32_e32 v1, 0x1800, v1
	global_load_dword v22, v0, s[8:9]
	global_load_dword v65, v1, s[8:9]
	v_add_u32_e32 v0, 0x1800, v0
	v_add_u32_e32 v1, 0x1800, v1
	global_load_dword v23, v0, s[8:9]
	global_load_dword v66, v1, s[8:9]
	v_add_u32_e32 v0, 0x1800, v0
	v_add_u32_e32 v1, 0x1800, v1
	global_load_dword v24, v0, s[8:9]
	global_load_dword v67, v1, s[8:9]
	v_add_u32_e32 v0, 0x1800, v0
	v_add_u32_e32 v1, 0x1800, v1
	global_load_dword v25, v0, s[8:9]
	global_load_dword v68, v1, s[8:9]
	v_add_u32_e32 v0, 0x1800, v0
	v_add_u32_e32 v1, 0x1800, v1
	global_load_dword v26, v0, s[8:9]
	global_load_dword v69, v1, s[8:9]
	v_add_u32_e32 v0, 0x1800, v0
	v_add_u32_e32 v1, 0x1800, v1
	global_load_dword v27, v0, s[8:9]
	global_load_dword v70, v1, s[8:9]
	v_add_u32_e32 v0, 0x1800, v0
	v_add_u32_e32 v1, 0x1800, v1
	global_load_dword v28, v0, s[8:9]
	global_load_dword v71, v1, s[8:9]
	v_add_u32_e32 v0, 0x1800, v0
	v_add_u32_e32 v1, 0x1800, v1
	global_load_dword v29, v0, s[8:9]
	global_load_dword v72, v1, s[8:9]
	v_add_u32_e32 v0, 0x1800, v0
	v_add_u32_e32 v1, 0x1800, v1
	global_load_dword v30, v0, s[8:9]
	global_load_dword v73, v1, s[8:9]
	v_add_u32_e32 v0, 0x1800, v0
	v_add_u32_e32 v1, 0x1800, v1
	global_load_dword v31, v0, s[8:9]
	global_load_dword v74, v1, s[8:9]
	v_add_u32_e32 v0, 0x1800, v0
	v_add_u32_e32 v1, 0x1800, v1
	global_load_dword v32, v0, s[8:9]
	global_load_dword v75, v1, s[8:9]
	v_add_u32_e32 v0, 0x1800, v0
	v_add_u32_e32 v1, 0x1800, v1
	s_waitcnt vmcnt(60)
	v_fmac_f32_e32 v45, 0, v2
	s_waitcnt vmcnt(58)
	v_fmac_f32_e32 v46, v45, v3
	s_waitcnt vmcnt(56)
	v_fmac_f32_e32 v47, v46, v4
	s_waitcnt vmcnt(54)
	v_fmac_f32_e32 v48, v47, v5
	s_waitcnt vmcnt(52)
	v_fmac_f32_e32 v49, v48, v6
	s_waitcnt vmcnt(50)
	v_fmac_f32_e32 v50, v49, v7
	s_waitcnt vmcnt(48)
	v_fmac_f32_e32 v51, v50, v8
	s_waitcnt vmcnt(46)
	v_fmac_f32_e32 v52, v51, v9
	s_waitcnt vmcnt(44)
	v_fmac_f32_e32 v53, v52, v10
	s_waitcnt vmcnt(42)
	v_fmac_f32_e32 v54, v53, v11
	s_waitcnt vmcnt(40)
	v_fmac_f32_e32 v55, v54, v12
	s_waitcnt vmcnt(38)
	v_fmac_f32_e32 v56, v55, v13
	global_load_dword v33, v0, s[8:9]
	global_load_dword v76, v1, s[8:9]
	v_add_u32_e32 v0, 0x1800, v0
	v_add_u32_e32 v1, 0x1800, v1
	global_load_dword v34, v0, s[8:9]
	global_load_dword v77, v1, s[8:9]
	v_add_u32_e32 v0, 0x1800, v0
	v_add_u32_e32 v1, 0x1800, v1
	global_load_dword v35, v0, s[8:9]
	global_load_dword v78, v1, s[8:9]
	v_add_u32_e32 v0, 0x1800, v0
	v_add_u32_e32 v1, 0x1800, v1
	global_load_dword v36, v0, s[8:9]
	global_load_dword v79, v1, s[8:9]
	v_add_u32_e32 v0, 0x1800, v0
	v_add_u32_e32 v1, 0x1800, v1
	global_load_dword v37, v0, s[8:9]
	global_load_dword v80, v1, s[8:9]
	v_add_u32_e32 v0, 0x1800, v0
	v_add_u32_e32 v1, 0x1800, v1
	global_load_dword v38, v0, s[8:9]
	global_load_dword v81, v1, s[8:9]
	v_add_u32_e32 v0, 0x1800, v0
	v_add_u32_e32 v1, 0x1800, v1
	global_load_dword v39, v0, s[8:9]
	global_load_dword v82, v1, s[8:9]
	v_add_u32_e32 v0, 0x1800, v0
	v_add_u32_e32 v1, 0x1800, v1
	global_load_dword v40, v0, s[8:9]
	global_load_dword v83, v1, s[8:9]
	v_add_u32_e32 v0, 0x1800, v0
	v_add_u32_e32 v1, 0x1800, v1
	global_load_dword v41, v0, s[8:9]
	global_load_dword v84, v1, s[8:9]
	v_add_u32_e32 v0, 0x1800, v0
	v_add_u32_e32 v1, 0x1800, v1
	global_load_dword v42, v0, s[8:9]
	global_load_dword v85, v1, s[8:9]
	v_add_u32_e32 v0, 0x1800, v0
	v_add_u32_e32 v1, 0x1800, v1
	global_load_dword v43, v0, s[8:9]
	global_load_dword v86, v1, s[8:9]
	v_add_u32_e32 v0, 0x1800, v0
	v_add_u32_e32 v1, 0x1800, v1
	global_load_dword v44, v0, s[8:9]
	global_load_dword v87, v1, s[8:9]
	v_add_u32_e32 v0, 0x1800, v0
	v_add_u32_e32 v1, 0x1800, v1
	s_waitcnt vmcnt(60)
	v_fmac_f32_e32 v57, v56, v14
	s_waitcnt vmcnt(58)
	v_fmac_f32_e32 v58, v57, v15
	s_waitcnt vmcnt(56)
	v_fmac_f32_e32 v59, v58, v16
	s_waitcnt vmcnt(54)
	v_fmac_f32_e32 v60, v59, v17
	s_waitcnt vmcnt(52)
	v_fmac_f32_e32 v61, v60, v18
	s_waitcnt vmcnt(50)
	v_fmac_f32_e32 v62, v61, v19
	s_waitcnt vmcnt(48)
	v_fmac_f32_e32 v63, v62, v20
	s_waitcnt vmcnt(46)
	v_fmac_f32_e32 v64, v63, v21
	s_waitcnt vmcnt(44)
	v_fmac_f32_e32 v65, v64, v22
	s_waitcnt vmcnt(42)
	v_fmac_f32_e32 v66, v65, v23
	s_waitcnt vmcnt(40)
	v_fmac_f32_e32 v67, v66, v24
	s_waitcnt vmcnt(38)
	v_fmac_f32_e32 v68, v67, v25
	s_waitcnt vmcnt(36)
	v_fmac_f32_e32 v69, v68, v26
	s_waitcnt vmcnt(34)
	v_fmac_f32_e32 v70, v69, v27
	s_waitcnt vmcnt(32)
	v_fmac_f32_e32 v71, v70, v28
	s_waitcnt vmcnt(30)
	v_fmac_f32_e32 v72, v71, v29
	s_waitcnt vmcnt(28)
	v_fmac_f32_e32 v73, v72, v30
	s_waitcnt vmcnt(26)
	v_fmac_f32_e32 v74, v73, v31
	s_waitcnt vmcnt(24)
	v_fmac_f32_e32 v75, v74, v32
	s_waitcnt vmcnt(22)
	v_fmac_f32_e32 v76, v75, v33
	s_waitcnt vmcnt(20)
	v_fmac_f32_e32 v77, v76, v34
	s_waitcnt vmcnt(18)
	v_fmac_f32_e32 v78, v77, v35
	s_waitcnt vmcnt(16)
	v_fmac_f32_e32 v79, v78, v36
	s_waitcnt vmcnt(14)
	v_fmac_f32_e32 v80, v79, v37
	s_waitcnt vmcnt(12)
	v_fmac_f32_e32 v81, v80, v38
	s_waitcnt vmcnt(10)
	v_fmac_f32_e32 v82, v81, v39
	s_waitcnt vmcnt(8)
	v_fmac_f32_e32 v83, v82, v40
	s_waitcnt vmcnt(6)
	v_fmac_f32_e32 v84, v83, v41
	s_waitcnt vmcnt(4)
	v_fmac_f32_e32 v85, v84, v42
	s_waitcnt vmcnt(2)
	v_fmac_f32_e32 v86, v85, v43
	s_waitcnt vmcnt(0)
	v_fmac_f32_e32 v87, v86, v44
	v_add_u32_e32 v0, 0x5cb800, v0
	global_store_dword v0, v173, s[8:9]
	v_add_u32_e32 v0, 0x1800, v0
	global_store_dword v0, v45, s[8:9]
	v_add_u32_e32 v0, 0x1800, v0
	global_store_dword v0, v46, s[8:9]
	v_add_u32_e32 v0, 0x1800, v0
	global_store_dword v0, v47, s[8:9]
	v_add_u32_e32 v0, 0x1800, v0
	global_store_dword v0, v48, s[8:9]
	v_add_u32_e32 v0, 0x1800, v0
	global_store_dword v0, v49, s[8:9]
	v_add_u32_e32 v0, 0x1800, v0
	global_store_dword v0, v50, s[8:9]
	v_add_u32_e32 v0, 0x1800, v0
	global_store_dword v0, v51, s[8:9]
	v_add_u32_e32 v0, 0x1800, v0
	global_store_dword v0, v52, s[8:9]
	v_add_u32_e32 v0, 0x1800, v0
	global_store_dword v0, v53, s[8:9]
	v_add_u32_e32 v0, 0x1800, v0
	global_store_dword v0, v54, s[8:9]
	v_add_u32_e32 v0, 0x1800, v0
	global_store_dword v0, v55, s[8:9]
	v_add_u32_e32 v0, 0x1800, v0
	global_store_dword v0, v56, s[8:9]
	v_add_u32_e32 v0, 0x1800, v0
	global_store_dword v0, v57, s[8:9]
	v_add_u32_e32 v0, 0x1800, v0
	global_store_dword v0, v58, s[8:9]
	v_add_u32_e32 v0, 0x1800, v0
	global_store_dword v0, v59, s[8:9]
	v_add_u32_e32 v0, 0x1800, v0
	global_store_dword v0, v60, s[8:9]
	v_add_u32_e32 v0, 0x1800, v0
	global_store_dword v0, v61, s[8:9]
	v_add_u32_e32 v0, 0x1800, v0
	global_store_dword v0, v62, s[8:9]
	v_add_u32_e32 v0, 0x1800, v0
	global_store_dword v0, v63, s[8:9]
	v_add_u32_e32 v0, 0x1800, v0
	global_store_dword v0, v64, s[8:9]
	v_add_u32_e32 v0, 0x1800, v0
	global_store_dword v0, v65, s[8:9]
	v_add_u32_e32 v0, 0x1800, v0
	global_store_dword v0, v66, s[8:9]
	v_add_u32_e32 v0, 0x1800, v0
	global_store_dword v0, v67, s[8:9]
	v_add_u32_e32 v0, 0x1800, v0
	global_store_dword v0, v68, s[8:9]
	v_add_u32_e32 v0, 0x1800, v0
	global_store_dword v0, v69, s[8:9]
	v_add_u32_e32 v0, 0x1800, v0
	global_store_dword v0, v70, s[8:9]
	v_add_u32_e32 v0, 0x1800, v0
	global_store_dword v0, v71, s[8:9]
	v_add_u32_e32 v0, 0x1800, v0
	global_store_dword v0, v72, s[8:9]
	v_add_u32_e32 v0, 0x1800, v0
	global_store_dword v0, v73, s[8:9]
	v_add_u32_e32 v0, 0x1800, v0
	global_store_dword v0, v74, s[8:9]
	v_add_u32_e32 v0, 0x1800, v0
	global_store_dword v0, v75, s[8:9]
	v_add_u32_e32 v0, 0x1800, v0
	global_store_dword v0, v76, s[8:9]
	v_add_u32_e32 v0, 0x1800, v0
	global_store_dword v0, v77, s[8:9]
	v_add_u32_e32 v0, 0x1800, v0
	global_store_dword v0, v78, s[8:9]
	v_add_u32_e32 v0, 0x1800, v0
	global_store_dword v0, v79, s[8:9]
	v_add_u32_e32 v0, 0x1800, v0
	global_store_dword v0, v80, s[8:9]
	v_add_u32_e32 v0, 0x1800, v0
	global_store_dword v0, v81, s[8:9]
	v_add_u32_e32 v0, 0x1800, v0
	global_store_dword v0, v82, s[8:9]
	v_add_u32_e32 v0, 0x1800, v0
	global_store_dword v0, v83, s[8:9]
	v_add_u32_e32 v0, 0x1800, v0
	global_store_dword v0, v84, s[8:9]
	v_add_u32_e32 v0, 0x1800, v0
	global_store_dword v0, v85, s[8:9]
	v_add_u32_e32 v0, 0x1800, v0
	global_store_dword v0, v86, s[8:9]
